# role-split (matrix beside VALU) attention fast loops: per step V2 | barrier | 16-24 MFMA segment at raised priority | barrier | exp segment, wave halves offset by one barrier interval
# speedup vs baseline: 1.0294x; 1.0259x over previous
.Lppk2_entry:
	v_readfirstlane_b32 s93, v234
	s_lshr_b32 s93, s93, 8
	s_cmp_eq_u32 s93, 0
	s_cbranch_scc1 .Lfsk2_260
	s_barrier
.Lfsk2_260:
	v_add_f32_e32 v230, v98, v99
	v_cvt_pk_bf16_f32 v150, v98, v99
	v_add_f32_e32 v231, v100, v101
	v_cvt_pk_bf16_f32 v151, v100, v101
	v_add_f32_e32 v230, v102, v230
	v_add_f32_e32 v231, v103, v231
	v_add_f32_e32 v230, v104, v230
	v_cvt_pk_bf16_f32 v152, v102, v103
	v_add_f32_e32 v231, v105, v231
	v_cvt_pk_bf16_f32 v153, v104, v105
	v_add_f32_e32 v230, v106, v230
	v_add_f32_e32 v231, v107, v231
	v_add_f32_e32 v230, v108, v230
	v_cvt_pk_bf16_f32 v10, v106, v107
	v_add_f32_e32 v231, v109, v231
	v_cvt_pk_bf16_f32 v11, v108, v109
	v_add_f32_e32 v230, v110, v230
	v_add_f32_e32 v231, v111, v231
	v_add_f32_e32 v230, v112, v230
	v_cvt_pk_bf16_f32 v12, v110, v111
	v_add_f32_e32 v231, v113, v231
	v_cvt_pk_bf16_f32 v13, v112, v113
	v_add_f32_e32 v230, v82, v230
	v_add_f32_e32 v231, v83, v231
	v_add_f32_e32 v230, v84, v230
	v_cvt_pk_bf16_f32 v6, v82, v83
	v_add_f32_e32 v231, v85, v231
	v_cvt_pk_bf16_f32 v7, v84, v85
	v_add_f32_e32 v230, v86, v230
	v_add_f32_e32 v231, v87, v231
	v_add_f32_e32 v230, v88, v230
	v_cvt_pk_bf16_f32 v8, v86, v87
	v_add_f32_e32 v231, v89, v231
	v_cvt_pk_bf16_f32 v9, v88, v89
	v_add_f32_e32 v230, v90, v230
	v_add_f32_e32 v231, v91, v231
	v_add_f32_e32 v230, v92, v230
	v_cvt_pk_bf16_f32 v2, v90, v91
	v_add_f32_e32 v231, v93, v231
	v_cvt_pk_bf16_f32 v3, v92, v93
	v_add_f32_e32 v230, v94, v230
	v_add_f32_e32 v231, v95, v231
	v_add_f32_e32 v230, v96, v230
	v_cvt_pk_bf16_f32 v4, v94, v95
	v_add_f32_e32 v231, v97, v231
	v_cvt_pk_bf16_f32 v5, v96, v97
	v_add_f32_e32 v230, v230, v231
	v_add_f32_e32 v206, v232, v230
	s_barrier
	s_setprio 1
	v_add_u32_e32 v0, s22, v251
	ds_read_b64_tr_b16 v[198:199], v0 offset:24576
	ds_read_b64_tr_b16 v[200:201], v0 offset:25088
	s_waitcnt lgkmcnt(9)
	v_mfma_f32_32x32x16_bf16 v[130:145], v[194:197], v[162:165], v[208:223]
	ds_read_b64_tr_b16 v[194:195], v0 offset:28672
	ds_read_b64_tr_b16 v[196:197], v0 offset:29184
	s_waitcnt lgkmcnt(10)
	v_mfma_f32_32x32x16_bf16 v[114:129], v[186:189], v[162:165], v[208:223]
	ds_read_b64_tr_b16 v[102:103], v0 offset:25600
	ds_read_b64_tr_b16 v[104:105], v0 offset:26112
	s_waitcnt lgkmcnt(11)
	v_mfma_f32_32x32x16_bf16 v[130:145], v[190:193], v[158:161], v[130:145]
	ds_read_b64_tr_b16 v[98:99], v0 offset:29696
	ds_read_b64_tr_b16 v[100:101], v0 offset:30208
	s_waitcnt lgkmcnt(12)
	v_mfma_f32_32x32x16_bf16 v[114:129], v[182:185], v[158:161], v[114:129]
	ds_read_b64_tr_b16 v[110:111], v0 offset:26624
	ds_read_b64_tr_b16 v[112:113], v0 offset:27136
	s_waitcnt lgkmcnt(13)
	v_mfma_f32_32x32x16_bf16 v[130:145], v[178:181], v[154:157], v[130:145]
	ds_read_b64_tr_b16 v[106:107], v0 offset:30720
	ds_read_b64_tr_b16 v[108:109], v0 offset:31232
	s_waitcnt lgkmcnt(14)
	v_mfma_f32_32x32x16_bf16 v[114:129], v[174:177], v[154:157], v[114:129]
	ds_read_b64_tr_b16 v[86:87], v0 offset:27648
	ds_read_b64_tr_b16 v[88:89], v0 offset:28160
	s_waitcnt lgkmcnt(14)
	v_mfma_f32_32x32x16_bf16 v[130:145], v[170:173], v[146:149], v[130:145]
	ds_read_b64_tr_b16 v[82:83], v0 offset:31744
	ds_read_b64_tr_b16 v[84:85], v0 offset:32256
	v_mfma_f32_32x32x16_bf16 v[114:129], v[166:169], v[146:149], v[114:129]
	s_add_u32 s54, s48, s14
	s_addc_u32 s55, s49, s15
	s_add_u32 s56, s54, 0x8000
	s_addc_u32 s57, s55, 0
	s_add_i32 s16, s21, s43
	s_mov_b32 m0, s16
	s_nop 0
	global_load_lds_dwordx4 v202, s[56:57]
	s_add_u32 s56, s50, s14
	s_addc_u32 s57, s51, s15
	s_add_u32 s56, s56, 0x4000
	s_addc_u32 s57, s57, 0
	s_add_i32 s16, s13, s44
	s_mov_b32 m0, s16
	s_nop 0
	global_load_lds_dwordx4 v203, s[56:57]
	s_add_u32 s58, s52, s14
	s_addc_u32 s59, s53, s15
	s_add_u32 s58, s58, 0x4000
	s_addc_u32 s59, s59, 0
	s_add_i32 s16, s13, s45
	s_mov_b32 m0, s16
	s_nop 0
	global_load_lds_dwordx4 v203, s[58:59]
	v_add_u32_e32 v0, s22, v249
	v_add_u32_e32 v166, 0xe800, v0
	s_waitcnt lgkmcnt(14)
	v_mfma_f32_32x32x16_bf16 v[66:81], v[150:153], v[198:201], v[66:81]
	ds_read_b64_tr_b16 v[90:91], v0 offset:59392
	ds_read_b64_tr_b16 v[92:93], v0 offset:59904
	s_waitcnt lgkmcnt(14)
	v_mfma_f32_32x32x16_bf16 v[50:65], v[150:153], v[194:197], v[50:65]
	ds_read_b64_tr_b16 v[94:95], v0 offset:63488
	ds_read_b64_tr_b16 v[96:97], v0 offset:64000
	s_waitcnt lgkmcnt(14)
	v_mfma_f32_32x32x16_bf16 v[66:81], v[10:13], v[102:105], v[66:81]
	ds_read_b64_tr_b16 v[102:103], v0 offset:60416
	ds_read_b64_tr_b16 v[104:105], v0 offset:60928
	s_waitcnt lgkmcnt(14)
	v_mfma_f32_32x32x16_bf16 v[50:65], v[10:13], v[98:101], v[50:65]
	ds_read_b64_tr_b16 v[98:99], v0 offset:64512
	ds_read_b64_tr_b16 v[100:101], v0 offset:65024
	s_waitcnt lgkmcnt(14)
	v_mfma_f32_32x32x16_bf16 v[66:81], v[6:9], v[110:113], v[66:81]
	ds_read_b64_tr_b16 v[110:111], v0 offset:61440
	ds_read_b64_tr_b16 v[112:113], v0 offset:61952
	s_waitcnt lgkmcnt(14)
	v_mfma_f32_32x32x16_bf16 v[50:65], v[6:9], v[106:109], v[50:65]
	ds_read_b64_tr_b16 v[106:107], v166 offset:6144
	ds_read_b64_tr_b16 v[108:109], v166 offset:6656
	s_waitcnt lgkmcnt(14)
	v_mfma_f32_32x32x16_bf16 v[66:81], v[2:5], v[86:89], v[66:81]
	ds_read_b64_tr_b16 v[190:191], v0 offset:62464
	ds_read_b64_tr_b16 v[192:193], v0 offset:62976
	s_waitcnt lgkmcnt(14)
	v_mfma_f32_32x32x16_bf16 v[50:65], v[2:5], v[82:85], v[50:65]
	ds_read_b64_tr_b16 v[194:195], v166 offset:7168
	ds_read_b64_tr_b16 v[196:197], v166 offset:7680
	s_waitcnt lgkmcnt(14)
	v_mfma_f32_32x32x16_bf16 v[34:49], v[150:153], v[90:93], v[34:49]
	s_waitcnt lgkmcnt(12)
	v_mfma_f32_32x32x16_bf16 v[18:33], v[150:153], v[94:97], v[18:33]
	v_add_u32_e32 v0, s13, v250
	ds_read_b128 v[86:89], v0
	ds_read_b128 v[82:85], v0 offset:512
	s_waitcnt lgkmcnt(12)
	v_mfma_f32_32x32x16_bf16 v[34:49], v[10:13], v[102:105], v[34:49]
	ds_read_b128 v[186:189], v0 offset:2048
	ds_read_b128 v[182:185], v0 offset:2560
	s_waitcnt lgkmcnt(12)
	v_mfma_f32_32x32x16_bf16 v[18:33], v[10:13], v[98:101], v[18:33]
	ds_read_b128 v[178:181], v0 offset:4096
	ds_read_b128 v[174:177], v0 offset:4608
	s_waitcnt lgkmcnt(12)
	v_mfma_f32_32x32x16_bf16 v[34:49], v[6:9], v[110:113], v[34:49]
	ds_read_b128 v[170:173], v0 offset:6144
	ds_read_b128 v[166:169], v0 offset:6656
	s_waitcnt lgkmcnt(12)
	v_mfma_f32_32x32x16_bf16 v[18:33], v[6:9], v[106:109], v[18:33]
	s_waitcnt lgkmcnt(10)
	v_mfma_f32_32x32x16_bf16 v[34:49], v[2:5], v[190:193], v[34:49]
	s_waitcnt lgkmcnt(8)
	v_mfma_f32_32x32x16_bf16 v[18:33], v[2:5], v[194:197], v[18:33]
	s_setprio 0
	s_waitcnt vmcnt(3) lgkmcnt(0)
	s_barrier
	v_exp_f32_e32 v130, v130
	v_exp_f32_e32 v131, v131
	v_exp_f32_e32 v132, v132
	v_exp_f32_e32 v133, v133
	v_exp_f32_e32 v134, v134
	v_exp_f32_e32 v135, v135
	v_exp_f32_e32 v136, v136
	v_exp_f32_e32 v137, v137
	v_exp_f32_e32 v138, v138
	v_exp_f32_e32 v139, v139
	v_exp_f32_e32 v140, v140
	v_exp_f32_e32 v141, v141
	v_exp_f32_e32 v142, v142
	v_exp_f32_e32 v143, v143
	v_exp_f32_e32 v144, v144
	v_exp_f32_e32 v145, v145
	v_exp_f32_e32 v114, v114
	v_exp_f32_e32 v115, v115
	v_exp_f32_e32 v116, v116
	v_exp_f32_e32 v117, v117
	v_exp_f32_e32 v118, v118
	v_exp_f32_e32 v119, v119
	v_exp_f32_e32 v120, v120
	v_exp_f32_e32 v121, v121
	v_exp_f32_e32 v122, v122
	v_exp_f32_e32 v123, v123
	v_exp_f32_e32 v124, v124
	v_exp_f32_e32 v125, v125
	v_exp_f32_e32 v126, v126
	v_exp_f32_e32 v127, v127
	v_exp_f32_e32 v128, v128
	v_exp_f32_e32 v129, v129
	v_add_f32_e32 v230, v130, v131
	v_cvt_pk_bf16_f32 v150, v130, v131
	v_add_f32_e32 v231, v132, v133
	v_cvt_pk_bf16_f32 v151, v132, v133
	v_add_f32_e32 v230, v134, v230
	v_add_f32_e32 v231, v135, v231
	v_add_f32_e32 v230, v136, v230
	v_cvt_pk_bf16_f32 v152, v134, v135
	v_add_f32_e32 v231, v137, v231
	v_cvt_pk_bf16_f32 v153, v136, v137
	v_add_f32_e32 v230, v138, v230
	v_add_f32_e32 v231, v139, v231
	v_add_f32_e32 v230, v140, v230
	v_cvt_pk_bf16_f32 v10, v138, v139
	v_add_f32_e32 v231, v141, v231
	v_cvt_pk_bf16_f32 v11, v140, v141
	v_add_f32_e32 v230, v142, v230
	v_add_f32_e32 v231, v143, v231
	v_add_f32_e32 v230, v144, v230
	v_cvt_pk_bf16_f32 v12, v142, v143
	v_add_f32_e32 v231, v145, v231
	v_cvt_pk_bf16_f32 v13, v144, v145
	v_add_f32_e32 v230, v114, v230
	v_add_f32_e32 v231, v115, v231
	v_add_f32_e32 v230, v116, v230
	v_cvt_pk_bf16_f32 v6, v114, v115
	v_add_f32_e32 v231, v117, v231
	v_cvt_pk_bf16_f32 v7, v116, v117
	v_add_f32_e32 v230, v118, v230
	v_add_f32_e32 v231, v119, v231
	v_add_f32_e32 v230, v120, v230
	v_cvt_pk_bf16_f32 v8, v118, v119
	v_add_f32_e32 v231, v121, v231
	v_cvt_pk_bf16_f32 v9, v120, v121
	v_add_f32_e32 v230, v122, v230
	v_add_f32_e32 v231, v123, v231
	v_add_f32_e32 v230, v124, v230
	v_cvt_pk_bf16_f32 v2, v122, v123
	v_add_f32_e32 v231, v125, v231
	v_cvt_pk_bf16_f32 v3, v124, v125
	v_add_f32_e32 v230, v126, v230
	v_add_f32_e32 v231, v127, v231
	v_add_f32_e32 v230, v128, v230
	v_cvt_pk_bf16_f32 v4, v126, v127
	v_add_f32_e32 v231, v129, v231
	v_cvt_pk_bf16_f32 v5, v128, v129
	v_add_f32_e32 v230, v230, v231
	v_add_f32_e32 v232, v206, v230
	s_barrier
;   #define WB(a,b) do{ if constexpr(DV2){WAIT_BAR(b);} else {WAIT_BAR(a);} }while(0)
;   #define RESC() do{ if(resc){ asm volatile("s_waitcnt lgkmcnt(0)":::"memory"); \
;       _Pragma("unroll") for(int d_=0;d_<ND;++d_) _Pragma("unroll") for(int r=0;r<16;++r)o[d_][r]*=wsf[crow(r,hi)]; } }while(0)
;   #define ROT() do{sl_prev=sl_cur;sl_cur=sl_next;sl_next=(sl_next==(NSLOT-1)*SLOTB)?0:sl_next+SLOTB;}while(0)
;     ...
;   int t=1;
;   for(;t+5<NT;t+=2){
;     STEP(pB0,pB1,pA0,pA1,t,true,true,true);     WB(2,3); RESC(); ROT();
;     STEP(pA0,pA1,pB0,pB1,t+1,true,true,true);   WB(2,3); RESC(); ROT();
;   }
	s_setprio 1
	s_add_i32 s16, s13, 0x2000
	s_cmpk_lg_i32 s13, 0x4000
	s_cselect_b32 s47, s16, 0
	v_add_u32_e32 v207, s21, v251
	ds_read_b64_tr_b16 v[198:199], v207 offset:24576
	ds_read_b64_tr_b16 v[200:201], v207 offset:25088
	s_waitcnt lgkmcnt(9)
	v_mfma_f32_32x32x16_bf16 v[98:113], v[86:89], v[162:165], v[208:223]
	ds_read_b64_tr_b16 v[194:195], v207 offset:28672
	ds_read_b64_tr_b16 v[196:197], v207 offset:29184
	s_waitcnt lgkmcnt(10)
	v_mfma_f32_32x32x16_bf16 v[82:97], v[82:85], v[162:165], v[208:223]
	ds_read_b64_tr_b16 v[190:191], v207 offset:25600
	ds_read_b64_tr_b16 v[192:193], v207 offset:26112
	s_waitcnt lgkmcnt(11)
	v_mfma_f32_32x32x16_bf16 v[98:113], v[186:189], v[158:161], v[98:113]
	ds_read_b64_tr_b16 v[138:139], v207 offset:29696
	ds_read_b64_tr_b16 v[140:141], v207 offset:30208
	s_waitcnt lgkmcnt(12)
	v_mfma_f32_32x32x16_bf16 v[82:97], v[182:185], v[158:161], v[82:97]
	ds_read_b64_tr_b16 v[134:135], v207 offset:26624
	ds_read_b64_tr_b16 v[136:137], v207 offset:27136
	s_waitcnt lgkmcnt(13)
	v_mfma_f32_32x32x16_bf16 v[98:113], v[178:181], v[154:157], v[98:113]
	ds_read_b64_tr_b16 v[130:131], v207 offset:30720
	ds_read_b64_tr_b16 v[132:133], v207 offset:31232
	s_waitcnt lgkmcnt(14)
	v_mfma_f32_32x32x16_bf16 v[82:97], v[174:177], v[154:157], v[82:97]
	ds_read_b64_tr_b16 v[118:119], v207 offset:27648
	ds_read_b64_tr_b16 v[120:121], v207 offset:28160
	s_waitcnt lgkmcnt(14)
	v_mfma_f32_32x32x16_bf16 v[98:113], v[170:173], v[146:149], v[98:113]
	ds_read_b64_tr_b16 v[114:115], v207 offset:31744
	ds_read_b64_tr_b16 v[116:117], v207 offset:32256
	v_mfma_f32_32x32x16_bf16 v[82:97], v[166:169], v[146:149], v[82:97]
	s_add_u32 s56, s54, 0xa000
	s_addc_u32 s57, s55, 0
	s_add_i32 s16, s13, s43
	s_mov_b32 m0, s16
	s_nop 0
	global_load_lds_dwordx4 v202, s[56:57]
	s_add_u32 s56, s50, s14
	s_addc_u32 s57, s51, s15
	s_add_u32 s56, s56, 0x6000
	s_addc_u32 s57, s57, 0
	s_add_i32 s16, s47, s44
	s_mov_b32 m0, s16
	s_nop 0
	global_load_lds_dwordx4 v203, s[56:57]
	s_add_u32 s58, s52, s14
	s_addc_u32 s59, s53, s15
	s_add_u32 s58, s58, 0x6000
	s_addc_u32 s59, s59, 0
	s_add_i32 s16, s47, s45
	s_mov_b32 m0, s16
	s_nop 0
	global_load_lds_dwordx4 v203, s[58:59]
	v_add_u32_e32 v14, s21, v249
	v_add_u32_e32 v15, 0xe800, v14
	s_waitcnt lgkmcnt(14)
	v_mfma_f32_32x32x16_bf16 v[66:81], v[150:153], v[198:201], v[66:81]
	ds_read_b64_tr_b16 v[122:123], v14 offset:59392
	ds_read_b64_tr_b16 v[124:125], v14 offset:59904
	s_waitcnt lgkmcnt(14)
	v_mfma_f32_32x32x16_bf16 v[50:65], v[150:153], v[194:197], v[50:65]
	ds_read_b64_tr_b16 v[126:127], v14 offset:63488
	ds_read_b64_tr_b16 v[128:129], v14 offset:64000
	s_waitcnt lgkmcnt(14)
	v_mfma_f32_32x32x16_bf16 v[66:81], v[10:13], v[190:193], v[66:81]
	ds_read_b64_tr_b16 v[142:143], v14 offset:60416
	ds_read_b64_tr_b16 v[144:145], v14 offset:60928
	s_waitcnt lgkmcnt(14)
	v_mfma_f32_32x32x16_bf16 v[50:65], v[10:13], v[138:141], v[50:65]
	ds_read_b64_tr_b16 v[138:139], v14 offset:64512
	ds_read_b64_tr_b16 v[140:141], v14 offset:65024
	s_waitcnt lgkmcnt(14)
	v_mfma_f32_32x32x16_bf16 v[66:81], v[6:9], v[134:137], v[66:81]
	ds_read_b64_tr_b16 v[134:135], v14 offset:61440
	ds_read_b64_tr_b16 v[136:137], v14 offset:61952
	s_waitcnt lgkmcnt(14)
	v_mfma_f32_32x32x16_bf16 v[50:65], v[6:9], v[130:133], v[50:65]
	ds_read_b64_tr_b16 v[130:131], v15 offset:6144
	ds_read_b64_tr_b16 v[132:133], v15 offset:6656
	s_waitcnt lgkmcnt(14)
	v_mfma_f32_32x32x16_bf16 v[66:81], v[2:5], v[118:121], v[66:81]
	ds_read_b64_tr_b16 v[118:119], v14 offset:62464
	ds_read_b64_tr_b16 v[120:121], v14 offset:62976
	s_waitcnt lgkmcnt(14)
	v_mfma_f32_32x32x16_bf16 v[50:65], v[2:5], v[114:117], v[50:65]
	ds_read_b64_tr_b16 v[114:115], v15 offset:7168
	ds_read_b64_tr_b16 v[116:117], v15 offset:7680
	s_waitcnt lgkmcnt(14)
	v_mfma_f32_32x32x16_bf16 v[34:49], v[150:153], v[122:125], v[34:49]
	s_waitcnt lgkmcnt(12)
	v_mfma_f32_32x32x16_bf16 v[18:33], v[150:153], v[126:129], v[18:33]
	v_add_u32_e32 v14, s47, v250
	ds_read_b128 v[194:197], v14
	ds_read_b128 v[186:189], v14 offset:512
	s_waitcnt lgkmcnt(12)
	v_mfma_f32_32x32x16_bf16 v[34:49], v[10:13], v[142:145], v[34:49]
	ds_read_b128 v[190:193], v14 offset:2048
	ds_read_b128 v[182:185], v14 offset:2560
	s_waitcnt lgkmcnt(12)
	v_mfma_f32_32x32x16_bf16 v[18:33], v[10:13], v[138:141], v[18:33]
	ds_read_b128 v[178:181], v14 offset:4096
	ds_read_b128 v[174:177], v14 offset:4608
	s_waitcnt lgkmcnt(12)
	v_mfma_f32_32x32x16_bf16 v[34:49], v[6:9], v[134:137], v[34:49]
	ds_read_b128 v[170:173], v14 offset:6144
	ds_read_b128 v[166:169], v14 offset:6656
	s_waitcnt lgkmcnt(12)
	v_mfma_f32_32x32x16_bf16 v[18:33], v[6:9], v[130:133], v[18:33]
	s_waitcnt lgkmcnt(10)
	v_mfma_f32_32x32x16_bf16 v[34:49], v[2:5], v[118:121], v[34:49]
	s_waitcnt lgkmcnt(8)
	v_mfma_f32_32x32x16_bf16 v[18:33], v[2:5], v[114:117], v[18:33]
	s_setprio 0
	s_waitcnt vmcnt(3) lgkmcnt(0)
	s_barrier
	v_exp_f32_e32 v98, v98
	v_exp_f32_e32 v99, v99
	v_exp_f32_e32 v100, v100
	v_exp_f32_e32 v101, v101
	v_exp_f32_e32 v102, v102
	v_exp_f32_e32 v103, v103
	v_exp_f32_e32 v104, v104
	v_exp_f32_e32 v105, v105
	v_exp_f32_e32 v106, v106
	v_exp_f32_e32 v107, v107
	v_exp_f32_e32 v108, v108
	v_exp_f32_e32 v109, v109
	v_exp_f32_e32 v110, v110
	v_exp_f32_e32 v111, v111
	v_exp_f32_e32 v112, v112
	v_exp_f32_e32 v113, v113
	v_exp_f32_e32 v82, v82
	v_exp_f32_e32 v83, v83
	v_exp_f32_e32 v84, v84
	v_exp_f32_e32 v85, v85
	v_exp_f32_e32 v86, v86
	v_exp_f32_e32 v87, v87
	v_exp_f32_e32 v88, v88
	v_exp_f32_e32 v89, v89
	v_exp_f32_e32 v90, v90
	v_exp_f32_e32 v91, v91
	v_exp_f32_e32 v92, v92
	v_exp_f32_e32 v93, v93
	v_exp_f32_e32 v94, v94
	v_exp_f32_e32 v95, v95
	v_exp_f32_e32 v96, v96
	v_exp_f32_e32 v97, v97
	s_add_i32 s16, s47, 0x2000
	s_cmpk_lg_i32 s47, 0x4000
	s_cselect_b32 s46, s16, 0
	s_add_i32 s16, s20, 2
	s_add_u32 s14, s14, 0x4000
	s_addc_u32 s15, s15, 0
	s_cmp_ge_u32 s16, s39
	s_cbranch_scc1 .Lppk2_exit
	s_mov_b32 s20, s16
	s_mov_b32 s22, s13
	s_mov_b32 s21, s47
	s_mov_b32 s13, s46
	s_branch .Lfsk2_260
.Lppk2_exit:
	s_cmp_lg_u32 s93, 0
	s_cbranch_scc1 .LBB0_281
	s_barrier
	s_branch .LBB0_281

.Lfsk0_840:
	v_add_f32_e32 v212, v82, v83
	v_cvt_pk_bf16_f32 v134, v82, v83
	v_add_f32_e32 v213, v84, v85
	v_cvt_pk_bf16_f32 v135, v84, v85
	v_add_f32_e32 v212, v86, v212
	v_add_f32_e32 v213, v87, v213
	v_add_f32_e32 v212, v88, v212
	v_cvt_pk_bf16_f32 v136, v86, v87
	v_add_f32_e32 v213, v89, v213
	v_cvt_pk_bf16_f32 v137, v88, v89
	v_add_f32_e32 v212, v90, v212
	v_add_f32_e32 v213, v91, v213
	v_add_f32_e32 v212, v92, v212
	v_cvt_pk_bf16_f32 v10, v90, v91
	v_add_f32_e32 v213, v93, v213
	v_cvt_pk_bf16_f32 v11, v92, v93
	v_add_f32_e32 v212, v94, v212
	v_add_f32_e32 v213, v95, v213
	v_add_f32_e32 v212, v96, v212
	v_cvt_pk_bf16_f32 v12, v94, v95
	v_add_f32_e32 v213, v97, v213
	v_cvt_pk_bf16_f32 v13, v96, v97
	v_add_f32_e32 v212, v66, v212
	v_add_f32_e32 v213, v67, v213
	v_add_f32_e32 v212, v68, v212
	v_cvt_pk_bf16_f32 v6, v66, v67
	v_add_f32_e32 v213, v69, v213
	v_cvt_pk_bf16_f32 v7, v68, v69
	v_add_f32_e32 v212, v70, v212
	v_add_f32_e32 v213, v71, v213
	v_add_f32_e32 v212, v72, v212
	v_cvt_pk_bf16_f32 v8, v70, v71
	v_add_f32_e32 v213, v73, v213
	v_cvt_pk_bf16_f32 v9, v72, v73
	v_add_f32_e32 v212, v74, v212
	v_add_f32_e32 v213, v75, v213
	v_add_f32_e32 v212, v76, v212
	v_cvt_pk_bf16_f32 v2, v74, v75
	v_add_f32_e32 v213, v77, v213
	v_cvt_pk_bf16_f32 v3, v76, v77
	v_add_f32_e32 v212, v78, v212
	v_add_f32_e32 v213, v79, v213
	v_add_f32_e32 v212, v80, v212
	v_cvt_pk_bf16_f32 v4, v78, v79
	v_add_f32_e32 v213, v81, v213
	v_cvt_pk_bf16_f32 v5, v80, v81
	v_add_f32_e32 v212, v212, v213
	v_add_f32_e32 v192, v206, v212
	s_barrier
	s_setprio 1
	v_add_u32_e32 v193, s8, v204
	ds_read_b64_tr_b16 v[182:183], v193 offset:24576
	ds_read_b64_tr_b16 v[184:185], v193 offset:25088
	s_waitcnt lgkmcnt(9)
	v_mfma_f32_32x32x16_bf16 v[114:129], v[178:181], v[146:149], v[50:65]
	ds_read_b64_tr_b16 v[178:179], v193 offset:28672
	ds_read_b64_tr_b16 v[180:181], v193 offset:29184
	s_waitcnt lgkmcnt(10)
	v_mfma_f32_32x32x16_bf16 v[98:113], v[174:177], v[146:149], v[50:65]
	ds_read_b64_tr_b16 v[82:83], v193 offset:25600
	ds_read_b64_tr_b16 v[84:85], v193 offset:26112
	s_waitcnt lgkmcnt(11)
	v_mfma_f32_32x32x16_bf16 v[114:129], v[170:173], v[142:145], v[114:129]
	ds_read_b64_tr_b16 v[86:87], v193 offset:29696
	ds_read_b64_tr_b16 v[88:89], v193 offset:30208
	s_waitcnt lgkmcnt(12)
	v_mfma_f32_32x32x16_bf16 v[98:113], v[166:169], v[142:145], v[98:113]
	ds_read_b64_tr_b16 v[90:91], v193 offset:26624
	ds_read_b64_tr_b16 v[92:93], v193 offset:27136
	s_waitcnt lgkmcnt(13)
	v_mfma_f32_32x32x16_bf16 v[114:129], v[162:165], v[138:141], v[114:129]
	ds_read_b64_tr_b16 v[66:67], v193 offset:30720
	ds_read_b64_tr_b16 v[68:69], v193 offset:31232
	s_waitcnt lgkmcnt(14)
	v_mfma_f32_32x32x16_bf16 v[98:113], v[158:161], v[138:141], v[98:113]
	ds_read_b64_tr_b16 v[70:71], v193 offset:27648
	ds_read_b64_tr_b16 v[72:73], v193 offset:28160
	s_waitcnt lgkmcnt(14)
	v_mfma_f32_32x32x16_bf16 v[114:129], v[154:157], v[130:133], v[114:129]
	ds_read_b64_tr_b16 v[74:75], v193 offset:31744
	ds_read_b64_tr_b16 v[76:77], v193 offset:32256
	v_mfma_f32_32x32x16_bf16 v[98:113], v[150:153], v[130:133], v[98:113]
	s_add_u32 s38, s34, s52
	s_addc_u32 s39, s35, s53
	s_add_i32 s8, s16, s26
	s_mov_b32 m0, s8
	s_nop 0
	global_load_lds_dwordx4 v208, s[38:39]
	s_add_u32 s40, s36, s52
	s_addc_u32 s41, s37, s53
	s_add_i32 s8, s14, s27
	s_mov_b32 m0, s8
	s_nop 0
	global_load_lds_dwordx4 v210, s[40:41]
	s_waitcnt lgkmcnt(14)
	v_mfma_f32_32x32x16_bf16 v[34:49], v[134:137], v[182:185], v[34:49]
	s_waitcnt lgkmcnt(12)
	v_mfma_f32_32x32x16_bf16 v[18:33], v[134:137], v[178:181], v[18:33]
	v_add_u32_e32 v94, s14, v203
	ds_read_b128 v[78:81], v94
	ds_read_b128 v[178:181], v94 offset:512
	s_waitcnt lgkmcnt(12)
	v_mfma_f32_32x32x16_bf16 v[34:49], v[10:13], v[82:85], v[34:49]
	ds_read_b128 v[182:185], v94 offset:2048
	ds_read_b128 v[174:177], v94 offset:2560
	s_waitcnt lgkmcnt(12)
	v_mfma_f32_32x32x16_bf16 v[18:33], v[10:13], v[86:89], v[18:33]
	ds_read_b128 v[170:173], v94 offset:4096
	ds_read_b128 v[166:169], v94 offset:4608
	s_waitcnt lgkmcnt(12)
	v_mfma_f32_32x32x16_bf16 v[34:49], v[6:9], v[90:93], v[34:49]
	ds_read_b128 v[162:165], v94 offset:6144
	ds_read_b128 v[158:161], v94 offset:6656
	s_waitcnt lgkmcnt(12)
	v_mfma_f32_32x32x16_bf16 v[18:33], v[6:9], v[66:69], v[18:33]
	s_waitcnt lgkmcnt(10)
	v_mfma_f32_32x32x16_bf16 v[34:49], v[2:5], v[70:73], v[34:49]
	s_waitcnt lgkmcnt(8)
	v_mfma_f32_32x32x16_bf16 v[18:33], v[2:5], v[74:77], v[18:33]
	s_setprio 0
	s_waitcnt vmcnt(2) lgkmcnt(0)
	s_barrier
;   #define WB(a,b) do{ if constexpr(DV2){WAIT_BAR(b);} else {WAIT_BAR(a);} }while(0)
;   #define RESC() do{ if(resc){ asm volatile("s_waitcnt lgkmcnt(0)":::"memory"); \
;       _Pragma("unroll") for(int d_=0;d_<ND;++d_) _Pragma("unroll") for(int r=0;r<16;++r)o[d_][r]*=wsf[crow(r,hi)]; } }while(0)
;   #define ROT() do{sl_prev=sl_cur;sl_cur=sl_next;sl_next=(sl_next==(NSLOT-1)*SLOTB)?0:sl_next+SLOTB;}while(0)
;     ...
;   int t=1;
;   for(;t+5<NT;t+=2){
;     STEP(pB0,pB1,pA0,pA1,t,true,true,true);     WB(2,3); RESC(); ROT();
;     STEP(pA0,pA1,pB0,pB1,t+1,true,true,true);   WB(2,3); RESC(); ROT();
;   }
	v_exp_f32_e32 v114, v114
	v_exp_f32_e32 v115, v115
	v_exp_f32_e32 v116, v116
	v_exp_f32_e32 v117, v117
	v_exp_f32_e32 v118, v118
	v_exp_f32_e32 v119, v119
	v_exp_f32_e32 v120, v120
	v_exp_f32_e32 v121, v121
	v_exp_f32_e32 v122, v122
	v_exp_f32_e32 v123, v123
	v_exp_f32_e32 v124, v124
	v_exp_f32_e32 v125, v125
	v_exp_f32_e32 v126, v126
	v_exp_f32_e32 v127, v127
	v_exp_f32_e32 v128, v128
	v_exp_f32_e32 v129, v129
	v_exp_f32_e32 v98, v98
	v_exp_f32_e32 v99, v99
	v_exp_f32_e32 v100, v100
	v_exp_f32_e32 v101, v101
	v_exp_f32_e32 v102, v102
	v_exp_f32_e32 v103, v103
	v_exp_f32_e32 v104, v104
	v_exp_f32_e32 v105, v105
	v_exp_f32_e32 v106, v106
	v_exp_f32_e32 v107, v107
	v_exp_f32_e32 v108, v108
	v_exp_f32_e32 v109, v109
	v_exp_f32_e32 v110, v110
	v_exp_f32_e32 v111, v111
	v_exp_f32_e32 v112, v112
	v_exp_f32_e32 v113, v113
	v_add_f32_e32 v212, v114, v115
	v_cvt_pk_bf16_f32 v134, v114, v115
	v_add_f32_e32 v213, v116, v117
	v_cvt_pk_bf16_f32 v135, v116, v117
	v_add_f32_e32 v212, v118, v212
	v_add_f32_e32 v213, v119, v213
	v_add_f32_e32 v212, v120, v212
	v_cvt_pk_bf16_f32 v136, v118, v119
	v_add_f32_e32 v213, v121, v213
	v_cvt_pk_bf16_f32 v137, v120, v121
	v_add_f32_e32 v212, v122, v212
	v_add_f32_e32 v213, v123, v213
	v_add_f32_e32 v212, v124, v212
	v_cvt_pk_bf16_f32 v10, v122, v123
	v_add_f32_e32 v213, v125, v213
	v_cvt_pk_bf16_f32 v11, v124, v125
	v_add_f32_e32 v212, v126, v212
	v_add_f32_e32 v213, v127, v213
	v_add_f32_e32 v212, v128, v212
	v_cvt_pk_bf16_f32 v12, v126, v127
	v_add_f32_e32 v213, v129, v213
	v_cvt_pk_bf16_f32 v13, v128, v129
	v_add_f32_e32 v212, v98, v212
	v_add_f32_e32 v213, v99, v213
	v_add_f32_e32 v212, v100, v212
	v_cvt_pk_bf16_f32 v6, v98, v99
	v_add_f32_e32 v213, v101, v213
	v_cvt_pk_bf16_f32 v7, v100, v101
	v_add_f32_e32 v212, v102, v212
	v_add_f32_e32 v213, v103, v213
	v_add_f32_e32 v212, v104, v212
	v_cvt_pk_bf16_f32 v8, v102, v103
	v_add_f32_e32 v213, v105, v213
	v_cvt_pk_bf16_f32 v9, v104, v105
	v_add_f32_e32 v212, v106, v212
	v_add_f32_e32 v213, v107, v213
	v_add_f32_e32 v212, v108, v212
	v_cvt_pk_bf16_f32 v2, v106, v107
	v_add_f32_e32 v213, v109, v213
	v_cvt_pk_bf16_f32 v3, v108, v109
	v_add_f32_e32 v212, v110, v212
	v_add_f32_e32 v213, v111, v213
	v_add_f32_e32 v212, v112, v212
	v_cvt_pk_bf16_f32 v4, v110, v111
	v_add_f32_e32 v213, v113, v213
	v_cvt_pk_bf16_f32 v5, v112, v113
	v_add_f32_e32 v212, v212, v213
	v_add_f32_e32 v206, v192, v212
	s_barrier
	s_setprio 1
	s_add_i32 s8, s14, 0x2000
	s_cmpk_lg_i32 s14, 0x4000
	s_cselect_b32 s28, s8, 0
	v_add_u32_e32 v194, s16, v204
	ds_read_b64_tr_b16 v[154:155], v194 offset:24576
	ds_read_b64_tr_b16 v[156:157], v194 offset:25088
	s_waitcnt lgkmcnt(9)
	v_mfma_f32_32x32x16_bf16 v[82:97], v[78:81], v[146:149], v[50:65]
	ds_read_b64_tr_b16 v[150:151], v194 offset:28672
	ds_read_b64_tr_b16 v[152:153], v194 offset:29184
	s_waitcnt lgkmcnt(10)
	v_mfma_f32_32x32x16_bf16 v[66:81], v[178:181], v[146:149], v[50:65]
	ds_read_b64_tr_b16 v[114:115], v194 offset:25600
	ds_read_b64_tr_b16 v[116:117], v194 offset:26112
	s_waitcnt lgkmcnt(11)
	v_mfma_f32_32x32x16_bf16 v[82:97], v[182:185], v[142:145], v[82:97]
	ds_read_b64_tr_b16 v[118:119], v194 offset:29696
	ds_read_b64_tr_b16 v[120:121], v194 offset:30208
	s_waitcnt lgkmcnt(12)
	v_mfma_f32_32x32x16_bf16 v[66:81], v[174:177], v[142:145], v[66:81]
	ds_read_b64_tr_b16 v[122:123], v194 offset:26624
	ds_read_b64_tr_b16 v[124:125], v194 offset:27136
	s_waitcnt lgkmcnt(13)
	v_mfma_f32_32x32x16_bf16 v[82:97], v[170:173], v[138:141], v[82:97]
	ds_read_b64_tr_b16 v[98:99], v194 offset:30720
	ds_read_b64_tr_b16 v[100:101], v194 offset:31232
	s_waitcnt lgkmcnt(14)
	v_mfma_f32_32x32x16_bf16 v[66:81], v[166:169], v[138:141], v[66:81]
	ds_read_b64_tr_b16 v[102:103], v194 offset:27648
	ds_read_b64_tr_b16 v[104:105], v194 offset:28160
	s_waitcnt lgkmcnt(14)
	v_mfma_f32_32x32x16_bf16 v[82:97], v[162:165], v[130:133], v[82:97]
	ds_read_b64_tr_b16 v[106:107], v194 offset:31744
	ds_read_b64_tr_b16 v[108:109], v194 offset:32256
	v_mfma_f32_32x32x16_bf16 v[66:81], v[158:161], v[130:133], v[66:81]
	s_add_i32 s8, s14, s26
	s_mov_b32 m0, s8
	s_nop 0
	global_load_lds_dwordx4 v208, s[34:35]
	s_add_i32 s8, s28, s27
	s_mov_b32 m0, s8
	s_nop 0
	global_load_lds_dwordx4 v210, s[36:37]
	s_waitcnt lgkmcnt(14)
	v_mfma_f32_32x32x16_bf16 v[34:49], v[134:137], v[154:157], v[34:49]
	s_waitcnt lgkmcnt(12)
	v_mfma_f32_32x32x16_bf16 v[18:33], v[134:137], v[150:153], v[18:33]
	v_add_u32_e32 v110, s28, v203
	ds_read_b128 v[178:181], v110
	ds_read_b128 v[174:177], v110 offset:512
	s_waitcnt lgkmcnt(12)
	v_mfma_f32_32x32x16_bf16 v[34:49], v[10:13], v[114:117], v[34:49]
	ds_read_b128 v[170:173], v110 offset:2048
	ds_read_b128 v[166:169], v110 offset:2560
	s_waitcnt lgkmcnt(12)
	v_mfma_f32_32x32x16_bf16 v[18:33], v[10:13], v[118:121], v[18:33]
	ds_read_b128 v[162:165], v110 offset:4096
	ds_read_b128 v[158:161], v110 offset:4608
	s_waitcnt lgkmcnt(12)
	v_mfma_f32_32x32x16_bf16 v[34:49], v[6:9], v[122:125], v[34:49]
	ds_read_b128 v[154:157], v110 offset:6144
	ds_read_b128 v[150:153], v110 offset:6656
	s_waitcnt lgkmcnt(12)
	v_mfma_f32_32x32x16_bf16 v[18:33], v[6:9], v[98:101], v[18:33]
	s_waitcnt lgkmcnt(10)
	v_mfma_f32_32x32x16_bf16 v[34:49], v[2:5], v[102:105], v[34:49]
	s_waitcnt lgkmcnt(8)
	v_mfma_f32_32x32x16_bf16 v[18:33], v[2:5], v[106:109], v[18:33]
	s_setprio 0
	s_waitcnt vmcnt(2) lgkmcnt(0)
	s_barrier
	v_exp_f32_e32 v82, v82
	v_exp_f32_e32 v83, v83
	v_exp_f32_e32 v84, v84
	v_exp_f32_e32 v85, v85
	v_exp_f32_e32 v86, v86
	v_exp_f32_e32 v87, v87
	v_exp_f32_e32 v88, v88
	v_exp_f32_e32 v89, v89
	v_exp_f32_e32 v90, v90
	v_exp_f32_e32 v91, v91
	v_exp_f32_e32 v92, v92
	v_exp_f32_e32 v93, v93
	v_exp_f32_e32 v94, v94
	v_exp_f32_e32 v95, v95
	v_exp_f32_e32 v96, v96
	v_exp_f32_e32 v97, v97
	v_exp_f32_e32 v66, v66
	v_exp_f32_e32 v67, v67
	v_exp_f32_e32 v68, v68
	v_exp_f32_e32 v69, v69
	v_exp_f32_e32 v70, v70
	v_exp_f32_e32 v71, v71
	v_exp_f32_e32 v72, v72
	v_exp_f32_e32 v73, v73
	v_exp_f32_e32 v74, v74
	v_exp_f32_e32 v75, v75
	v_exp_f32_e32 v76, v76
	v_exp_f32_e32 v77, v77
	v_exp_f32_e32 v78, v78
	v_exp_f32_e32 v79, v79
	v_exp_f32_e32 v80, v80
	v_exp_f32_e32 v81, v81
	s_add_i32 s8, s28, 0x2000
	s_cmpk_lg_i32 s28, 0x4000
	s_cselect_b32 s29, s8, 0
	s_add_i32 s8, s15, 2
	s_add_u32 s36, s36, 0x4000
	s_addc_u32 s37, s37, 0
	s_add_u32 s34, s34, 0x4000
	s_addc_u32 s35, s35, 0
	s_cmp_ge_u32 s8, s25
	s_cbranch_scc1 .Lppk0_exit
	s_mov_b32 s15, s8
	s_mov_b32 s8, s14
	s_mov_b32 s16, s28
	s_mov_b32 s14, s29
	s_branch .Lfsk0_840
